# v58 + even-layer pair norm: class-B tasks assigned per XCD (own two batches), so op 2's grid sync is XCD-local in every layer
# speedup vs baseline: 1.0110x; 1.0016x over previous
; DI void norm_pair_phase(Frame& F, const float* srcL, const float* srcC, const float* g, const float* modl, int sub) {
;     ...
;     const int NT_L = NB * 2049, NT = NT_L + TC / 2;
;     for (int task = gw; task < NT; task += NGW) {
;         int bi, r1, r2, j; bool single, isc = task >= NT_L;
;         if (!isc) { bi = task / 2049; j = task % 2049; single = (j == 0 || j == 2048); r1 = bi * SEQ + j; r2 = single ? r1 : bi * SEQ + SEQ - j; }
;         else { bi = 16; j = 0; single = false; r1 = TL + 2 * (task - NT_L); r2 = r1 + 1; }
.Lpn_classB:
	s_sub_u32 s4, s4, 8
	s_lshl_b32 s4, s4, 3
	s_add_u32 s4, s4, s50
	s_mul_i32 s5, s5, 0x1002
	s_add_u32 s2, s4, s5
	s_add_u32 s101, s5, 0x1001
	s_movk_i32 s10, 0xc0
	s_mov_b32 s99, 1
	s_lshl_b32 s3, s10, 1
	s_sub_i32 s17, 0x1000, s2
	s_lshl_b32 s4, s2, 1
	s_sub_i32 s18, s4, 31

; #define GRID_SYNC() do { nbar += (unsigned)gridDim.x; grid_barrier(barw, nbar); } while (0)
; DI void grid_barrier(unsigned* cnt, unsigned target) {
;     asm volatile("s_waitcnt vmcnt(0) lgkmcnt(0)" ::: "memory");
;     __syncthreads();
;     if (threadIdx.x == 0) {
;         __builtin_amdgcn_fence(__ATOMIC_RELEASE, "agent");
;         asm volatile("s_waitcnt vmcnt(0)" ::: "memory");
;         __hip_atomic_fetch_add(cnt, 1u, __ATOMIC_RELAXED, __HIP_MEMORY_SCOPE_AGENT);
;         while (__hip_atomic_load(cnt, __ATOMIC_RELAXED, __HIP_MEMORY_SCOPE_AGENT) < target) __builtin_amdgcn_s_sleep(2);
;         __builtin_amdgcn_fence(__ATOMIC_ACQUIRE, "agent");
;         asm volatile("s_waitcnt vmcnt(0)" ::: "memory");
;     }
;     __syncthreads();
; }
; __global__ void __launch_bounds__(512, 2) fwd_megakernel(Args args) {
;     ...
;             if (!(op == 4 || op == 6 || op == 7 || skip0)) GRID_SYNC();
.Lcs_b_normal:
	s_waitcnt lgkmcnt(0)
	s_cmp_eq_u32 s13, 0x100
	s_cbranch_scc0 .Lxl_no
	s_cmp_eq_u32 s44, 2
	s_cbranch_scc0 .Lxl_not2
	s_branch .Lxl_yes
